# v24 + merge-GEMM k-loops use the paired staging order as well
# baseline (speedup 1.0000x reference)
; DI f32x4 mfma16(bf16x8 a, bf16x8 b, f32x4 c) { return __builtin_amdgcn_mfma_f32_16x16x32_bf16(a, b, c, 0, 0, 0); }
; DI void merge_tile(const Params& p, int layer, int tm, int tn, bf16_t* smem) {
;     ...
;   auto gload_next = [&]() {
;     const bf16_t* ab = la + (size_t)lkt * laks; const bf16_t* bb = lb + (size_t)lkt * 64;
; #pragma unroll
;     for (int i = 0; i < 4; ++i) ra[i] = *(const u32x4*)(ab + pa0 + (size_t)i * 64 * lald);
; #pragma unroll
;     for (int i = 0; i < 2; ++i) rb[i] = *(const u32x4*)(bb + pb0 + (size_t)i * 64 * lbld);
;     if (++lkt == lnk) {
;       if (ls + 1 < 6) { ++ls; lkt = 0; get_seg(ls); set_offsets(); } else lkt = lnk - 1;
;     }
;   };
;   auto sstore = [&](int buf) {
;     bf16_t* As = smem + buf * L::STAGE; bf16_t* Bs = As + L::A_ELEMS;
; #pragma unroll
;     for (int i = 0; i < 4; ++i) { const int c = tid + NTHR * i; *(u32x4*)(As + (c >> 3) * LDT + (c & 7) * 8) = ra[i]; }
; #pragma unroll
;     for (int i = 0; i < 2; ++i) { const int c = tid + NTHR * i; *(u32x4*)(Bs + (c >> 3) * LDT + (c & 7) * 8) = rb[i]; }
;   };
;   gload_next(); sstore(0); gload_next(); __syncthreads();
;   int buf = 0;
; #pragma unroll 1
;   for (int sg = 0; sg < 6; ++sg) {
;     const int nk = (sg & 1) ? 8 : 16;
; #pragma unroll 1
;     for (int kt = 0; kt < nk; ++kt) {
;       sstore(buf ^ 1);
;       gload_next();
;       __builtin_amdgcn_sched_barrier(0);
;       const bf16_t* As = smem + buf * L::STAGE + (wm * 128 + l15) * LDT + quad * 8;
;       const bf16_t* Bs = smem + buf * L::STAGE + L::A_ELEMS + (wn * 32 + l15) * LDT + quad * 8;
; #pragma unroll
;       for (int ks = 0; ks < 2; ++ks) {
;         if (ks == 1) asm volatile("" ::: "memory");
;         bf16x8 b[2];
; #pragma unroll
;         for (int j = 0; j < 2; ++j) b[j] = *(const bf16x8*)(Bs + j * 16 * LDT + ks * 32);
; #pragma unroll
;         for (int i = 0; i < 8; ++i) {
;           const bf16x8 a = *(const bf16x8*)(As + i * 16 * LDT + ks * 32);
; #pragma unroll
;           for (int j = 0; j < 2; ++j) acc[i][j] = mfma16(b[j], a, acc[i][j]);
;         }
;       }
;       __syncthreads();
.Lmg0_main:
	ds_read_b128 v[178:181], v165 offset:9216
	s_waitcnt lgkmcnt(2)
	v_mfma_f32_16x16x32_bf16 v[148:151], v[152:155], v[156:159], v[148:151]
	s_xor_b32 s44, s45, 1
	s_mul_i32 s15, s44, 0xd800
	v_add3_u32 v202, s15, v232, v229
	s_waitcnt vmcnt(5)
	ds_write_b128 v202, v[4:7]
	s_waitcnt lgkmcnt(2)
	v_mfma_f32_16x16x32_bf16 v[144:147], v[160:163], v[156:159], v[144:147]
	ds_read_b128 v[182:185], v165 offset:11520
	ds_read_b128 v[194:197], v164 offset:36928
	ds_read_b128 v[198:201], v164 offset:39232
	v_mfma_f32_16x16x32_bf16 v[140:143], v[152:155], v[166:169], v[140:143]
	v_mfma_f32_16x16x32_bf16 v[136:139], v[160:163], v[166:169], v[136:139]
	ds_read_b128 v[186:189], v165 offset:13824
	v_mfma_f32_16x16x32_bf16 v[132:135], v[152:155], v[170:173], v[132:135]
	v_add3_u32 v203, s15, v233, v229
	s_waitcnt vmcnt(4)
	ds_write_b128 v203, v[0:3]
	v_mfma_f32_16x16x32_bf16 v[128:131], v[160:163], v[170:173], v[128:131]
	ds_read_b128 v[190:193], v165 offset:16128
	v_mfma_f32_16x16x32_bf16 v[124:127], v[152:155], v[174:177], v[124:127]
	s_ashr_i32 s21, s20, 31
	s_mul_i32 s46, s41, s21
	v_add3_u32 v204, s15, v234, v229
	v_add3_u32 v205, s15, v235, v229
	s_mul_hi_u32 s15, s41, s20
	s_add_i32 s47, s15, s46
	s_mul_i32 s46, s41, s20
	s_lshl_b64 s[46:47], s[46:47], 1
	s_add_u32 s46, s18, s46
	s_addc_u32 s47, s19, s47
	v_lshl_add_u64 v[0:1], v[216:217], 1, s[46:47]
	s_nop 0
	global_load_dwordx4 v[4:7], v[0:1], off
	s_lshl_b64 s[46:47], s[2:3], 7
	v_lshl_add_u64 v[206:207], v[0:1], 0, s[46:47]
	s_nop 0
	global_load_dwordx4 v[0:3], v[206:207], off
	v_mfma_f32_16x16x32_bf16 v[120:123], v[160:163], v[174:177], v[120:123]
	s_waitcnt vmcnt(5)
	ds_write_b128 v204, v[12:15]
	ds_read_b128 v[156:159], v165 offset:64
	s_waitcnt lgkmcnt(9)
	v_mfma_f32_16x16x32_bf16 v[116:119], v[152:155], v[178:181], v[116:119]
	v_mfma_f32_16x16x32_bf16 v[112:115], v[160:163], v[178:181], v[112:115]
	v_lshl_add_u64 v[206:207], v[206:207], 0, s[46:47]
	s_nop 0
	global_load_dwordx4 v[12:15], v[206:207], off
	ds_read_b128 v[166:169], v165 offset:2368
	s_waitcnt lgkmcnt(8)
	v_mfma_f32_16x16x32_bf16 v[108:111], v[152:155], v[182:185], v[108:111]
	v_mfma_f32_16x16x32_bf16 v[104:107], v[160:163], v[182:185], v[104:107]
	s_waitcnt vmcnt(5)
	ds_write_b128 v205, v[8:11]
	ds_read_b128 v[170:173], v165 offset:4672
	s_waitcnt lgkmcnt(7)
	v_mfma_f32_16x16x32_bf16 v[100:103], v[152:155], v[186:189], v[100:103]
	v_mfma_f32_16x16x32_bf16 v[96:99], v[160:163], v[186:189], v[96:99]
	v_lshl_add_u64 v[208:209], v[206:207], 0, s[46:47]
	s_nop 0
	global_load_dwordx4 v[8:11], v[208:209], off
	ds_read_b128 v[174:177], v165 offset:6976
	s_waitcnt lgkmcnt(6)
	v_mfma_f32_16x16x32_bf16 v[92:95], v[152:155], v[190:193], v[92:95]
	v_mfma_f32_16x16x32_bf16 v[88:91], v[160:163], v[190:193], v[88:91]
	s_waitcnt vmcnt(5)
	ds_write_b128 v202, v[16:19] offset:36864
	ds_read_b128 v[178:181], v165 offset:9280
	s_waitcnt lgkmcnt(6)
	v_mfma_f32_16x16x32_bf16 v[148:151], v[194:197], v[156:159], v[148:151]
	v_mfma_f32_16x16x32_bf16 v[144:147], v[198:201], v[156:159], v[144:147]
	ds_read_b128 v[182:185], v165 offset:11584
	s_waitcnt lgkmcnt(6)
	v_mfma_f32_16x16x32_bf16 v[140:143], v[194:197], v[166:169], v[140:143]
	s_waitcnt vmcnt(4)
	ds_write_b128 v203, v[20:23] offset:36864
	v_mfma_f32_16x16x32_bf16 v[136:139], v[198:201], v[166:169], v[136:139]
	ds_read_b128 v[186:189], v165 offset:13888
	s_waitcnt lgkmcnt(6)
	v_mfma_f32_16x16x32_bf16 v[132:135], v[194:197], v[170:173], v[132:135]
	s_lshl_b64 s[48:49], s[20:21], 7
	s_add_u32 s46, s16, s48
	s_addc_u32 s47, s17, s49
	v_mov_b32_e32 v219, v217
	v_lshl_add_u64 v[16:17], v[218:219], 1, s[46:47]
	s_mov_b32 s15, s3
	s_lshl_b64 s[46:47], s[14:15], 7
	v_lshl_add_u64 v[20:21], v[16:17], 0, s[46:47]
	s_nop 0
	global_load_dwordx4 v[16:19], v[16:17], off
	s_nop 0
	global_load_dwordx4 v[20:23], v[20:21], off
	v_mfma_f32_16x16x32_bf16 v[128:131], v[198:201], v[170:173], v[128:131]
	ds_read_b128 v[190:193], v165 offset:16192
	s_waitcnt lgkmcnt(6)
	v_mfma_f32_16x16x32_bf16 v[124:127], v[194:197], v[174:177], v[124:127]
	v_mfma_f32_16x16x32_bf16 v[120:123], v[198:201], v[174:177], v[120:123]
	s_waitcnt lgkmcnt(0)
	s_barrier
	s_add_i32 s15, s20, 1
	s_cmp_lg_u32 s15, s42
	s_cbranch_scc1 .LBB0_842
	s_cmp_gt_i32 s43, 4
	s_cbranch_scc1 .LBB0_845
	s_add_i32 s21, s43, 1
	s_ashr_i32 s18, s21, 1
	s_bitcmp0_b32 s43, 0
	s_mov_b64 s[14:15], -1
	s_cbranch_scc1 .LBB0_840
	s_ashr_i32 s19, s18, 31
	s_lshl_b64 s[14:15], s[18:19], 21
	s_add_u32 s16, s10, s14
	s_addc_u32 s17, s11, s15
	s_mov_b64 s[14:15], 0

; DI f32x4 mfma16(bf16x8 a, bf16x8 b, f32x4 c) { return __builtin_amdgcn_mfma_f32_16x16x32_bf16(a, b, c, 0, 0, 0); }
; DI void merge_tile(const Params& p, int layer, int tm, int tn, bf16_t* smem) {
;     ...
;   auto gload_next = [&]() {
;     const bf16_t* ab = la + (size_t)lkt * laks; const bf16_t* bb = lb + (size_t)lkt * 64;
; #pragma unroll
;     for (int i = 0; i < 4; ++i) ra[i] = *(const u32x4*)(ab + pa0 + (size_t)i * 64 * lald);
; #pragma unroll
;     for (int i = 0; i < 2; ++i) rb[i] = *(const u32x4*)(bb + pb0 + (size_t)i * 64 * lbld);
;     if (++lkt == lnk) {
;       if (ls + 1 < 6) { ++ls; lkt = 0; get_seg(ls); set_offsets(); } else lkt = lnk - 1;
;     }
;   };
;   auto sstore = [&](int buf) {
;     bf16_t* As = smem + buf * L::STAGE; bf16_t* Bs = As + L::A_ELEMS;
; #pragma unroll
;     for (int i = 0; i < 4; ++i) { const int c = tid + NTHR * i; *(u32x4*)(As + (c >> 3) * LDT + (c & 7) * 8) = ra[i]; }
; #pragma unroll
;     for (int i = 0; i < 2; ++i) { const int c = tid + NTHR * i; *(u32x4*)(Bs + (c >> 3) * LDT + (c & 7) * 8) = rb[i]; }
;   };
;   gload_next(); sstore(0); gload_next(); __syncthreads();
;   int buf = 0;
; #pragma unroll 1
;   for (int sg = 0; sg < 6; ++sg) {
;     const int nk = (sg & 1) ? 8 : 16;
; #pragma unroll 1
;     for (int kt = 0; kt < nk; ++kt) {
;       sstore(buf ^ 1);
;       gload_next();
;       __builtin_amdgcn_sched_barrier(0);
;       const bf16_t* As = smem + buf * L::STAGE + (wm * 128 + l15) * LDT + quad * 8;
;       const bf16_t* Bs = smem + buf * L::STAGE + L::A_ELEMS + (wn * 32 + l15) * LDT + quad * 8;
; #pragma unroll
;       for (int ks = 0; ks < 2; ++ks) {
;         if (ks == 1) asm volatile("" ::: "memory");
;         bf16x8 b[2];
; #pragma unroll
;         for (int j = 0; j < 2; ++j) b[j] = *(const bf16x8*)(Bs + j * 16 * LDT + ks * 32);
; #pragma unroll
;         for (int i = 0; i < 8; ++i) {
;           const bf16x8 a = *(const bf16x8*)(As + i * 16 * LDT + ks * 32);
; #pragma unroll
;           for (int j = 0; j < 2; ++j) acc[i][j] = mfma16(b[j], a, acc[i][j]);
;         }
;       }
;       __syncthreads();
.Lmg1_main:
	ds_read_b128 v[182:185], v168 offset:9216
	s_waitcnt lgkmcnt(2)
	v_mfma_f32_16x16x32_bf16 v[148:151], v[152:155], v[156:159], v[148:151]
	s_xor_b32 s55, s57, 1
	s_mul_i32 s2, s55, 0xd800
	v_add3_u32 v169, s2, v232, v229
	s_waitcnt vmcnt(5)
	ds_write_b128 v169, v[4:7]
	s_waitcnt lgkmcnt(2)
	v_mfma_f32_16x16x32_bf16 v[144:147], v[160:163], v[156:159], v[144:147]
	ds_read_b128 v[186:189], v168 offset:11520
	ds_read_b128 v[198:201], v164 offset:36928
	ds_read_b128 v[202:205], v164 offset:39232
	v_mfma_f32_16x16x32_bf16 v[140:143], v[152:155], v[170:173], v[140:143]
	v_mfma_f32_16x16x32_bf16 v[136:139], v[160:163], v[170:173], v[136:139]
	ds_read_b128 v[190:193], v168 offset:13824
	v_mfma_f32_16x16x32_bf16 v[132:135], v[152:155], v[174:177], v[132:135]
	v_add3_u32 v206, s2, v233, v229
	s_waitcnt vmcnt(4)
	ds_write_b128 v206, v[0:3]
	v_mfma_f32_16x16x32_bf16 v[128:131], v[160:163], v[174:177], v[128:131]
	ds_read_b128 v[194:197], v168 offset:16128
	v_mfma_f32_16x16x32_bf16 v[124:127], v[152:155], v[178:181], v[124:127]
	v_add3_u32 v207, s2, v234, v229
	v_add3_u32 v208, s2, v235, v229
	s_mul_hi_u32 s2, s52, s26
	s_ashr_i32 s27, s26, 31
	s_mul_i32 s3, s52, s27
	s_add_i32 s3, s2, s3
	s_mul_i32 s2, s52, s26
	s_lshl_b64 s[2:3], s[2:3], 1
	s_add_u32 s2, s24, s2
	s_addc_u32 s3, s25, s3
	v_lshl_add_u64 v[0:1], v[216:217], 1, s[2:3]
	s_nop 0
	global_load_dwordx4 v[4:7], v[0:1], off
	s_lshl_b64 s[2:3], s[8:9], 7
	v_lshl_add_u64 v[210:211], v[0:1], 0, s[2:3]
	s_nop 0
	global_load_dwordx4 v[0:3], v[210:211], off
	v_mfma_f32_16x16x32_bf16 v[120:123], v[160:163], v[178:181], v[120:123]
	s_waitcnt vmcnt(5)
	ds_write_b128 v207, v[12:15]
	ds_read_b128 v[156:159], v168 offset:64
	s_waitcnt lgkmcnt(9)
	v_mfma_f32_16x16x32_bf16 v[116:119], v[152:155], v[182:185], v[116:119]
	v_mfma_f32_16x16x32_bf16 v[112:115], v[160:163], v[182:185], v[112:115]
	v_lshl_add_u64 v[210:211], v[210:211], 0, s[2:3]
	s_nop 0
	global_load_dwordx4 v[12:15], v[210:211], off
	ds_read_b128 v[170:173], v168 offset:2368
	s_waitcnt lgkmcnt(8)
	v_mfma_f32_16x16x32_bf16 v[108:111], v[152:155], v[186:189], v[108:111]
	v_mfma_f32_16x16x32_bf16 v[104:107], v[160:163], v[186:189], v[104:107]
	s_waitcnt vmcnt(5)
	ds_write_b128 v208, v[8:11]
	ds_read_b128 v[174:177], v168 offset:4672
	s_waitcnt lgkmcnt(7)
	v_mfma_f32_16x16x32_bf16 v[100:103], v[152:155], v[190:193], v[100:103]
	v_mfma_f32_16x16x32_bf16 v[96:99], v[160:163], v[190:193], v[96:99]
	v_lshl_add_u64 v[212:213], v[210:211], 0, s[2:3]
	s_nop 0
	global_load_dwordx4 v[8:11], v[212:213], off
	ds_read_b128 v[178:181], v168 offset:6976
	s_waitcnt lgkmcnt(6)
	v_mfma_f32_16x16x32_bf16 v[92:95], v[152:155], v[194:197], v[92:95]
	v_mfma_f32_16x16x32_bf16 v[88:91], v[160:163], v[194:197], v[88:91]
	s_waitcnt vmcnt(5)
	ds_write_b128 v169, v[16:19] offset:36864
	ds_read_b128 v[182:185], v168 offset:9280
	s_waitcnt lgkmcnt(6)
	v_mfma_f32_16x16x32_bf16 v[148:151], v[198:201], v[156:159], v[148:151]
	v_mfma_f32_16x16x32_bf16 v[144:147], v[202:205], v[156:159], v[144:147]
	ds_read_b128 v[186:189], v168 offset:11584
	s_waitcnt lgkmcnt(6)
	v_mfma_f32_16x16x32_bf16 v[140:143], v[198:201], v[170:173], v[140:143]
	s_waitcnt vmcnt(4)
	ds_write_b128 v206, v[20:23] offset:36864
	v_mfma_f32_16x16x32_bf16 v[136:139], v[202:205], v[170:173], v[136:139]
	ds_read_b128 v[190:193], v168 offset:13888
	s_waitcnt lgkmcnt(6)
	v_mfma_f32_16x16x32_bf16 v[132:135], v[198:201], v[174:177], v[132:135]
	s_lshl_b64 s[4:5], s[26:27], 7
	s_add_u32 s2, s22, s4
	s_addc_u32 s3, s23, s5
	v_mov_b32_e32 v219, v217
	v_lshl_add_u64 v[16:17], v[218:219], 1, s[2:3]
	s_mov_b32 s21, s9
	s_lshl_b64 s[2:3], s[20:21], 7
	v_lshl_add_u64 v[20:21], v[16:17], 0, s[2:3]
	s_nop 0
	global_load_dwordx4 v[16:19], v[16:17], off
	s_nop 0
	global_load_dwordx4 v[20:23], v[20:21], off
	v_mfma_f32_16x16x32_bf16 v[128:131], v[202:205], v[174:177], v[128:131]
	ds_read_b128 v[194:197], v168 offset:16192
	s_waitcnt lgkmcnt(6)
	v_mfma_f32_16x16x32_bf16 v[124:127], v[198:201], v[178:181], v[124:127]
	v_mfma_f32_16x16x32_bf16 v[120:123], v[202:205], v[178:181], v[120:123]
	s_waitcnt lgkmcnt(0)
	s_barrier
	s_add_i32 s2, s26, 1
	s_cmp_lg_u32 s2, s53
	s_cbranch_scc1 .LBB0_1876
	s_cmp_gt_i32 s54, 4
	s_cbranch_scc1 .LBB0_1879
	s_add_i32 s21, s54, 1
	s_ashr_i32 s2, s21, 1
	s_bitcmp0_b32 s54, 0
	s_mov_b64 s[4:5], -1
	s_cbranch_scc1 .LBB0_1874
	s_ashr_i32 s3, s2, 31
	s_lshl_b64 s[4:5], s[2:3], 21
	s_add_u32 s22, s16, s4
	s_addc_u32 s23, s17, s5
	s_mov_b64 s[4:5], 0
